# LN2 second pass: all gamma/beta loads of a row issued before the variance reduction and consumed with counted waits instead of a load/wait/store ladder
# speedup vs baseline: 1.0076x; 1.0041x over previous
.LBB0_1822:
	s_or_b64 exec, exec, s[24:25]
	v_pk_add_f32 v[10:11], v[72:73], v[24:25]
	v_pk_add_f32 v[22:23], v[70:71], v[26:27]
	s_waitcnt vmcnt(2)
	v_add_f32_e32 v13, v16, v17
	v_pk_add_f32 v[10:11], v[10:11], v[22:23]
	v_add_f32_e32 v69, v18, v19
	v_add_f32_e32 v11, 0, v11
	v_add_f32_e32 v67, v10, v11
	v_pk_add_f32 v[10:11], v[76:77], v[20:21]
	v_pk_add_f32 v[22:23], v[12:13], v[68:69]
	v_pk_add_f32 v[10:11], v[10:11], v[10:11] op_sel_hi:[0,1]
	v_mov_b32_e32 v15, v11
	v_pk_add_f32 v[10:11], v[14:15], v[66:67]
	s_waitcnt vmcnt(1)
	v_add_f32_e32 v79, v0, v1
	v_pk_add_f32 v[10:11], v[22:23], v[10:11]
	v_pk_add_f32 v[22:23], v[74:75], v[8:9]
	v_pk_add_f32 v[10:11], v[10:11], v[10:11] op_sel_hi:[0,1]
	v_pk_add_f32 v[22:23], v[22:23], v[22:23] op_sel_hi:[0,1]
	v_add_f32_e32 v81, v2, v3
	s_waitcnt vmcnt(0)
	v_mov_b32_e32 v78, v4
	v_mov_b32_e32 v80, v5
	v_mov_b32_e32 v22, v6
	v_mov_b32_e32 v10, v7
	v_pk_add_f32 v[78:79], v[78:79], v[80:81]
	v_pk_add_f32 v[10:11], v[22:23], v[10:11]
	v_xor_b32_e32 v13, 1, v92
	v_pk_add_f32 v[10:11], v[78:79], v[10:11]
	v_mov_b32_e32 v61, v29
	v_add_f32_e32 v10, v10, v11
	v_and_b32_e32 v11, 64, v92
	v_add_u32_e32 v11, 64, v11
	v_cmp_lt_i32_e32 vcc, v13, v11
	v_mov_b32_e32 v63, v29
	s_nop 0
	v_cndmask_b32_e32 v13, v92, v13, vcc
	v_lshlrev_b32_e32 v13, 2, v13
	ds_bpermute_b32 v15, v13, v10
	s_waitcnt lgkmcnt(0)
	v_add_f32_e32 v10, v10, v15
	v_xor_b32_e32 v15, 2, v92
	v_cmp_lt_i32_e32 vcc, v15, v11
	s_nop 1
	v_cndmask_b32_e32 v15, v92, v15, vcc
	v_lshlrev_b32_e32 v15, 2, v15
	ds_bpermute_b32 v22, v15, v10
	s_waitcnt lgkmcnt(0)
	v_add_f32_e32 v10, v10, v22
	v_xor_b32_e32 v22, 4, v92
	v_cmp_lt_i32_e32 vcc, v22, v11
	s_nop 1
	v_cndmask_b32_e32 v22, v92, v22, vcc
	v_lshlrev_b32_e32 v51, 2, v22
	ds_bpermute_b32 v22, v51, v10
	s_waitcnt lgkmcnt(0)
	v_add_f32_e32 v10, v10, v22
	v_xor_b32_e32 v22, 8, v92
	v_cmp_lt_i32_e32 vcc, v22, v11
	s_nop 1
	v_cndmask_b32_e32 v22, v92, v22, vcc
	v_lshlrev_b32_e32 v53, 2, v22
	ds_bpermute_b32 v22, v53, v10
	s_waitcnt lgkmcnt(0)
	v_add_f32_e32 v10, v10, v22
	v_xor_b32_e32 v22, 16, v92
	v_cmp_lt_i32_e32 vcc, v22, v11
	s_nop 1
	v_cndmask_b32_e32 v22, v92, v22, vcc
	v_lshlrev_b32_e32 v55, 2, v22
	ds_bpermute_b32 v22, v55, v10
	s_waitcnt lgkmcnt(0)
	v_add_f32_e32 v10, v10, v22
	v_xor_b32_e32 v22, 32, v92
	v_cmp_lt_i32_e32 vcc, v22, v11
	s_nop 1
	v_cndmask_b32_e32 v11, v92, v22, vcc
	v_lshlrev_b32_e32 v57, 2, v11
	ds_bpermute_b32 v11, v57, v10
	s_waitcnt lgkmcnt(0)
	v_add_f32_e32 v59, v10, v11
	v_fmac_f32_e32 v25, 0xba000000, v59
	v_fmac_f32_e32 v24, 0xba000000, v59
	v_fmac_f32_e32 v27, 0xba000000, v59
	v_fmac_f32_e32 v73, 0xba000000, v59
	v_fmac_f32_e32 v26, 0xba000000, v59
	v_fmac_f32_e32 v72, 0xba000000, v59
	v_mov_b32_e32 v22, v25
	v_mov_b32_e32 v23, v24
	v_fmac_f32_e32 v71, 0xba000000, v59
	v_fmac_f32_e32 v70, 0xba000000, v59
	v_mov_b32_e32 v10, v73
	v_mov_b32_e32 v11, v72
	v_pk_mul_f32 v[22:23], v[22:23], v[22:23]
	v_mov_b32_e32 v78, v27
	v_mov_b32_e32 v79, v26
	v_pk_fma_f32 v[10:11], v[10:11], v[10:11], v[22:23]
	v_mov_b32_e32 v22, v71
	v_mov_b32_e32 v23, v70
	v_pk_mul_f32 v[78:79], v[78:79], v[78:79]
	v_fmac_f32_e32 v76, 0xba000000, v59
	v_pk_fma_f32 v[22:23], v[22:23], v[22:23], v[78:79]
	v_fmac_f32_e32 v21, 0xba000000, v59
	v_fmac_f32_e32 v77, 0xba000000, v59
	v_pk_add_f32 v[10:11], v[10:11], v[22:23]
	v_fmac_f32_e32 v20, 0xba000000, v59
	v_mov_b32_e32 v84, v77
	v_mov_b32_e32 v85, v21
	v_mov_b32_e32 v21, v76
	v_pk_add_f32 v[10:11], v[10:11], v[10:11] op_sel_hi:[0,1]
	v_pk_mul_f32 v[22:23], v[84:85], v[84:85]
	v_pk_mul_f32 v[76:77], v[20:21], v[20:21]
	v_fmac_f32_e32 v16, 0xba000000, v59
	v_pk_mov_b32 v[78:79], v[76:77], v[22:23] op_sel:[1,0]
	v_mov_b32_e32 v77, v23
	v_fmac_f32_e32 v17, 0xba000000, v59
	v_fmac_f32_e32 v18, 0xba000000, v59
	v_mul_f32_e32 v10, v16, v16
	v_pk_add_f32 v[22:23], v[78:79], v[76:77]
	v_fmac_f32_e32 v19, 0xba000000, v59
	v_pk_fma_f32 v[76:77], v[16:17], v[16:17], v[10:11] op_sel_hi:[1,1,0]
	v_mul_f32_e32 v10, v18, v18
	v_pk_add_f32 v[22:23], v[22:23], v[22:23] op_sel_hi:[0,1]
	v_pk_fma_f32 v[78:79], v[18:19], v[18:19], v[10:11] op_sel_hi:[1,1,0]
	v_fmac_f32_e32 v66, 0xba000000, v59
	v_fmac_f32_e32 v14, 0xba000000, v59
	v_fmac_f32_e32 v68, 0xba000000, v59
	v_fmac_f32_e32 v12, 0xba000000, v59
	v_mul_f32_e32 v76, v12, v12
	v_mul_f32_e32 v78, v68, v68
	v_mul_f32_e32 v22, v14, v14
	v_mul_f32_e32 v10, v66, v66
	v_pk_add_f32 v[76:77], v[76:77], v[78:79]
	v_pk_add_f32 v[10:11], v[22:23], v[10:11]
	v_fmac_f32_e32 v74, 0xba000000, v59
	v_pk_add_f32 v[10:11], v[76:77], v[10:11]
	global_load_dwordx4 v[76:79], v[30:31], off
	global_load_dwordx4 v[80:83], v[32:33], off
	global_load_dwordx4 v[96:99], v[30:31], off offset:1024
	global_load_dwordx4 v[100:103], v[32:33], off offset:1024
	global_load_dwordx4 v[104:107], v[30:31], off offset:2048
	global_load_dwordx4 v[108:111], v[32:33], off offset:2048
	global_load_dwordx4 v[112:115], v[30:31], off offset:3072
	global_load_dwordx4 v[116:119], v[32:33], off offset:3072
	global_load_dwordx4 v[120:123], v[34:35], off
	global_load_dwordx4 v[124:127], v[36:37], off
	global_load_dwordx4 v[128:131], v[38:39], off
	global_load_dwordx4 v[132:135], v[40:41], off
	global_load_dwordx4 v[136:139], v[42:43], off
	global_load_dwordx4 v[140:143], v[44:45], off
	global_load_dwordx4 v[144:147], v[46:47], off
	global_load_dwordx4 v[148:151], v[48:49], off
	v_fmac_f32_e32 v9, 0xba000000, v59
	v_fmac_f32_e32 v75, 0xba000000, v59
	v_fmac_f32_e32 v8, 0xba000000, v59
	v_mov_b32_e32 v86, v75
	v_mov_b32_e32 v87, v9
	v_mov_b32_e32 v9, v74
	v_pk_add_f32 v[10:11], v[10:11], v[10:11] op_sel_hi:[0,1]
	v_pk_mul_f32 v[22:23], v[86:87], v[86:87]
	v_pk_mul_f32 v[74:75], v[8:9], v[8:9]
	v_fmamk_f32 v0, v59, 0xba000000, v0
	v_pk_mov_b32 v[88:89], v[74:75], v[22:23] op_sel:[1,0]
	v_mov_b32_e32 v75, v23
	v_fmamk_f32 v1, v59, 0xba000000, v1
	v_fmac_f32_e32 v2, 0xba000000, v59
	v_mul_f32_e32 v10, v0, v0
	v_pk_add_f32 v[22:23], v[88:89], v[74:75]
	v_fmamk_f32 v3, v59, 0xba000000, v3
	v_pk_fma_f32 v[74:75], v[0:1], v[0:1], v[10:11] op_sel_hi:[1,1,0]
	v_mul_f32_e32 v10, v2, v2
	v_pk_add_f32 v[22:23], v[22:23], v[22:23] op_sel_hi:[0,1]
	v_pk_fma_f32 v[88:89], v[2:3], v[2:3], v[10:11] op_sel_hi:[1,1,0]
	v_fmamk_f32 v95, v59, 0xba000000, v7
	v_fmamk_f32 v94, v59, 0xba000000, v6
	v_fmamk_f32 v5, v59, 0xba000000, v5
	v_fmac_f32_e32 v4, 0xba000000, v59
	v_mul_f32_e32 v74, v4, v4
	v_mul_f32_e32 v88, v5, v5
	v_mul_f32_e32 v22, v94, v94
	v_mul_f32_e32 v10, v95, v95
	v_pk_add_f32 v[6:7], v[74:75], v[88:89]
	v_pk_add_f32 v[10:11], v[22:23], v[10:11]
	v_mov_b32_e32 v59, v29
	v_pk_add_f32 v[6:7], v[6:7], v[10:11]
	v_mov_b32_e32 v11, v27
	v_add_f32_e32 v6, v6, v7
	ds_bpermute_b32 v7, v13, v6
	s_waitcnt lgkmcnt(0)
	v_add_f32_e32 v6, v6, v7
	ds_bpermute_b32 v7, v15, v6
	s_waitcnt lgkmcnt(0)
	v_add_f32_e32 v6, v6, v7
	ds_bpermute_b32 v7, v51, v6
	s_waitcnt lgkmcnt(0)
	v_add_f32_e32 v6, v6, v7
	ds_bpermute_b32 v7, v53, v6
	s_waitcnt lgkmcnt(0)
	v_add_f32_e32 v6, v6, v7
	ds_bpermute_b32 v7, v55, v6
	s_waitcnt lgkmcnt(0)
	v_add_f32_e32 v7, v6, v7
	ds_bpermute_b32 v10, v57, v7
	v_mov_b32_e32 v6, v73
	v_mov_b32_e32 v73, v24
	v_mov_b32_e32 v57, v29
	s_waitcnt lgkmcnt(0)
	v_add_f32_e32 v7, v7, v10
	v_fmamk_f32 v7, v7, 0x3a000000, v91
	v_mul_f32_e32 v10, 0x4b800000, v7
	v_cmp_gt_f32_e32 vcc, s29, v7
	s_nop 1
	v_cndmask_b32_e32 v7, v7, v10, vcc
	v_rsq_f32_e32 v13, v7
	v_mov_b32_e32 v7, v25
	v_mov_b32_e32 v10, v71
	v_mov_b32_e32 v71, v26
	v_mul_f32_e32 v15, 0x45800000, v13
	v_cndmask_b32_e32 v88, v13, v15, vcc
	v_pk_mul_f32 v[6:7], v[6:7], v[88:89] op_sel_hi:[1,0]
	v_pk_mul_f32 v[10:11], v[10:11], v[88:89] op_sel_hi:[1,0]
	s_waitcnt vmcnt(14)
	v_pk_fma_f32 v[76:77], v[76:77], v[6:7], v[80:81]
	v_pk_fma_f32 v[78:79], v[78:79], v[10:11], v[82:83]
	v_lshl_add_u64 v[6:7], v[64:65], 0, v[28:29]
	global_store_dwordx4 v[6:7], v[76:79], off
	v_pk_mul_f32 v[10:11], v[70:71], v[88:89] op_sel_hi:[1,0]
	v_pk_mul_f32 v[22:23], v[72:73], v[88:89] op_sel_hi:[1,0]
	v_pk_mul_f32 v[20:21], v[20:21], v[88:89] op_sel_hi:[1,0]
	v_pk_mul_f32 v[16:17], v[16:17], v[88:89] op_sel_hi:[1,0]
	v_mov_b32_e32 v15, v66
	v_mov_b32_e32 v13, v68
	v_pk_mul_f32 v[14:15], v[14:15], v[88:89] op_sel_hi:[1,0]
	v_pk_mul_f32 v[2:3], v[2:3], v[88:89] op_sel_hi:[1,0]
	v_pk_mul_f32 v[0:1], v[0:1], v[88:89] op_sel_hi:[1,0]
	v_pk_mul_f32 v[4:5], v[4:5], v[88:89] op_sel_hi:[1,0]
	s_waitcnt vmcnt(13)
	v_pk_fma_f32 v[22:23], v[96:97], v[22:23], v[100:101]
	v_pk_fma_f32 v[24:25], v[98:99], v[10:11], v[102:103]
	global_store_dwordx4 v[6:7], v[22:25], off offset:1024
	v_pk_mul_f32 v[10:11], v[84:85], v[88:89] op_sel_hi:[1,0]
	s_waitcnt vmcnt(12)
	v_pk_fma_f32 v[20:21], v[104:105], v[20:21], v[108:109]
	v_pk_fma_f32 v[22:23], v[106:107], v[10:11], v[110:111]
	global_store_dwordx4 v[6:7], v[20:23], off offset:2048
	v_pk_mul_f32 v[10:11], v[18:19], v[88:89] op_sel_hi:[1,0]
	s_waitcnt vmcnt(11)
	v_pk_fma_f32 v[16:17], v[112:113], v[16:17], v[116:117]
	v_pk_fma_f32 v[18:19], v[114:115], v[10:11], v[118:119]
	global_store_dwordx4 v[6:7], v[16:19], off offset:3072
	v_pk_mul_f32 v[10:11], v[12:13], v[88:89] op_sel_hi:[1,0]
	v_lshl_add_u64 v[6:7], v[64:65], 0, v[56:57]
	s_waitcnt vmcnt(10)
	v_pk_fma_f32 v[10:11], v[120:121], v[10:11], v[124:125]
	v_pk_fma_f32 v[12:13], v[122:123], v[14:15], v[126:127]
	global_store_dwordx4 v[6:7], v[10:13], off
	s_nop 1
	v_pk_mul_f32 v[20:21], v[86:87], v[88:89] op_sel_hi:[1,0]
	v_pk_mul_f32 v[6:7], v[8:9], v[88:89] op_sel_hi:[1,0]
	v_lshl_add_u64 v[18:19], v[64:65], 0, v[58:59]
	s_waitcnt vmcnt(9)
	v_pk_fma_f32 v[6:7], v[128:129], v[6:7], v[132:133]
	v_pk_fma_f32 v[8:9], v[130:131], v[20:21], v[134:135]
	global_store_dwordx4 v[18:19], v[6:9], off
	v_lshl_add_u64 v[14:15], v[64:65], 0, v[60:61]
	s_waitcnt vmcnt(8)
	v_pk_fma_f32 v[0:1], v[136:137], v[0:1], v[140:141]
	v_pk_fma_f32 v[2:3], v[138:139], v[2:3], v[142:143]
	global_store_dwordx4 v[14:15], v[0:3], off
	v_pk_mul_f32 v[10:11], v[94:95], v[88:89] op_sel_hi:[1,0]
	s_waitcnt vmcnt(7)
	v_pk_fma_f32 v[152:153], v[144:145], v[4:5], v[148:149]
	v_pk_fma_f32 v[154:155], v[146:147], v[10:11], v[150:151]
	v_lshl_add_u64 v[4:5], v[64:65], 0, v[62:63]
	global_store_dwordx4 v[4:5], v[152:155], off
